# speedup vs baseline: 1.0095x; 1.0095x over previous
; DEV int TID() { int t = threadIdx.x; asm volatile("" : "+v"(t)); return t; }
; PHASE void lru_carry_phase(const float* __restrict__ LA, const float* __restrict__ LH, float* __restrict__ LC) {
;   for (int i = blockIdx.x * 256 + TID(); i < 4096; i += gridDim.x * 256) {
;     const int b = i >> 11, ch = i & 2047;
;     float h = 0.f;
; #pragma unroll 8
;     for (int c = 0; c < 256; ++c) {
;       size_t idx = ((size_t)b * 256 + c) * 2048 + ch;
;       LC[idx] = h;
;       h = LA[idx] * h + LH[idx];
;     }
;   }
; }
.LBB0_353:
	v_ashrrev_i32_e32 v0, 11, v4
	v_ashrrev_i32_e32 v1, 31, v0
	v_and_b32_e32 v2, 0x7ff, v5
	v_lshlrev_b64 v[0:1], 21, v[0:1]
	v_lshl_or_b32 v0, v2, 2, v0
	v_lshl_add_u64 v[0:1], s[46:47], 0, v[0:1]
	v_mov_b32_e32 v6, 0
	s_mov_b64 s[6:7], 0
	v_add_co_u32_e32 v26, vcc, 0x28850000, v0
	s_nop 1
	v_addc_co_u32_e32 v27, vcc, 0, v1, vcc
	v_add_co_u32_e32 v28, vcc, 0x28c50000, v0
	s_nop 1
	v_addc_co_u32_e32 v29, vcc, 0, v1, vcc
	v_add_co_u32_e32 v30, vcc, 0x29050000, v0
	s_nop 1
	v_addc_co_u32_e32 v31, vcc, 0, v1, vcc
	v_mov_b32_e32 v32, 0x2000
	v_mov_b32_e32 v33, 0
.LBB0_354:
	global_load_dword v10, v[26:27], off
	global_load_dword v18, v[28:29], off
	v_lshl_add_u64 v[26:27], v[26:27], 0, v[32:33]
	v_lshl_add_u64 v[28:29], v[28:29], 0, v[32:33]
	global_load_dword v11, v[26:27], off
	global_load_dword v19, v[28:29], off
	v_lshl_add_u64 v[26:27], v[26:27], 0, v[32:33]
	v_lshl_add_u64 v[28:29], v[28:29], 0, v[32:33]
	global_load_dword v12, v[26:27], off
	global_load_dword v20, v[28:29], off
	v_lshl_add_u64 v[26:27], v[26:27], 0, v[32:33]
	v_lshl_add_u64 v[28:29], v[28:29], 0, v[32:33]
	global_load_dword v13, v[26:27], off
	global_load_dword v21, v[28:29], off
	v_lshl_add_u64 v[26:27], v[26:27], 0, v[32:33]
	v_lshl_add_u64 v[28:29], v[28:29], 0, v[32:33]
	global_load_dword v14, v[26:27], off
	global_load_dword v22, v[28:29], off
	v_lshl_add_u64 v[26:27], v[26:27], 0, v[32:33]
	v_lshl_add_u64 v[28:29], v[28:29], 0, v[32:33]
	global_load_dword v15, v[26:27], off
	global_load_dword v23, v[28:29], off
	v_lshl_add_u64 v[26:27], v[26:27], 0, v[32:33]
	v_lshl_add_u64 v[28:29], v[28:29], 0, v[32:33]
	global_load_dword v16, v[26:27], off
	global_load_dword v24, v[28:29], off
	v_lshl_add_u64 v[26:27], v[26:27], 0, v[32:33]
	v_lshl_add_u64 v[28:29], v[28:29], 0, v[32:33]
	global_load_dword v17, v[26:27], off
	global_load_dword v25, v[28:29], off
	v_lshl_add_u64 v[26:27], v[26:27], 0, v[32:33]
	v_lshl_add_u64 v[28:29], v[28:29], 0, v[32:33]
	s_add_u32 s6, s6, 0x10000
	s_addc_u32 s7, s7, 0
	s_waitcnt vmcnt(0)
	global_store_dword v[30:31], v6, off
	v_lshl_add_u64 v[30:31], v[30:31], 0, v[32:33]
	v_fmac_f32_e32 v18, v6, v10
	global_store_dword v[30:31], v18, off
	v_lshl_add_u64 v[30:31], v[30:31], 0, v[32:33]
	v_fmac_f32_e32 v19, v18, v11
	global_store_dword v[30:31], v19, off
	v_lshl_add_u64 v[30:31], v[30:31], 0, v[32:33]
	v_fmac_f32_e32 v20, v19, v12
	global_store_dword v[30:31], v20, off
	v_lshl_add_u64 v[30:31], v[30:31], 0, v[32:33]
	v_fmac_f32_e32 v21, v20, v13
	global_store_dword v[30:31], v21, off
	v_lshl_add_u64 v[30:31], v[30:31], 0, v[32:33]
	v_fmac_f32_e32 v22, v21, v14
	global_store_dword v[30:31], v22, off
	v_lshl_add_u64 v[30:31], v[30:31], 0, v[32:33]
	v_fmac_f32_e32 v23, v22, v15
	global_store_dword v[30:31], v23, off
	v_lshl_add_u64 v[30:31], v[30:31], 0, v[32:33]
	v_fmac_f32_e32 v24, v23, v16
	global_store_dword v[30:31], v24, off
	v_lshl_add_u64 v[30:31], v[30:31], 0, v[32:33]
	v_fmac_f32_e32 v25, v24, v17
	v_mov_b32_e32 v6, v25
	s_cmp_eq_u32 s6, 0x200000
	s_cbranch_scc0 .LBB0_354
	v_add_u32_e32 v4, s8, v4
	s_movk_i32 s6, 0xfff
	v_cmp_lt_i32_e32 vcc, s6, v4
	s_or_b64 s[4:5], vcc, s[4:5]
	v_add_u16_e32 v5, s8, v5
	s_andn2_b64 exec, exec, s[4:5]
	s_cbranch_execnz .LBB0_353

; PHASE void idx_select_phase(const float* __restrict__ SC, int* __restrict__ SEL, int* __restrict__ DUMP, int chunk, unsigned char* smem) {
;     ...
;           const unsigned cand = vv | (1u << bit);
;           int c2 = 0;
; #pragma unroll
;           for (int q = 0; q < 32; ++q) c2 += (ck[q] >= cand) ? 1 : 0;
;           int tot = 0;
; #pragma unroll
;           for (int bb = 0; bb < 6; ++bb) tot += __popcll(__ballot((c2 >> bb) & 1)) << bb;
;           if (tot >= 256) vv = cand;
;         }
.LBB0_987:
	s_add_i32 s0, s5, -2
	s_lshl_b32 s0, 1, s0
	s_or_b32 s8, s0, s4
	s_waitcnt lgkmcnt(0)
	s_mov_b32 m0, 0
	v_cmp_le_u32_e64 s[0:1], s8, v12
	v_cmp_le_u32_e32 vcc, s8, v13
	s_bcnt1_i32_b64 s0, s[0:1]
	s_bcnt1_i32_b64 s1, vcc
	s_add_i32 m0, m0, s0
	s_add_i32 m0, m0, s1
	v_cmp_le_u32_e64 s[0:1], s8, v15
	v_cmp_le_u32_e32 vcc, s8, v14
	s_bcnt1_i32_b64 s0, s[0:1]
	s_bcnt1_i32_b64 s1, vcc
	s_add_i32 m0, m0, s0
	s_add_i32 m0, m0, s1
	v_cmp_le_u32_e64 s[0:1], s8, v17
	v_cmp_le_u32_e32 vcc, s8, v16
	s_bcnt1_i32_b64 s0, s[0:1]
	s_bcnt1_i32_b64 s1, vcc
	s_add_i32 m0, m0, s0
	s_add_i32 m0, m0, s1
	v_cmp_le_u32_e64 s[0:1], s8, v198
	v_cmp_le_u32_e32 vcc, s8, v156
	s_bcnt1_i32_b64 s0, s[0:1]
	s_bcnt1_i32_b64 s1, vcc
	s_add_i32 m0, m0, s0
	s_add_i32 m0, m0, s1
	v_cmp_le_u32_e64 s[0:1], s8, v200
	v_cmp_le_u32_e32 vcc, s8, v199
	s_bcnt1_i32_b64 s0, s[0:1]
	s_bcnt1_i32_b64 s1, vcc
	s_add_i32 m0, m0, s0
	s_add_i32 m0, m0, s1
	v_cmp_le_u32_e64 s[0:1], s8, v202
	v_cmp_le_u32_e32 vcc, s8, v201
	s_bcnt1_i32_b64 s0, s[0:1]
	s_bcnt1_i32_b64 s1, vcc
	s_add_i32 m0, m0, s0
	s_add_i32 m0, m0, s1
	v_cmp_le_u32_e64 s[0:1], s8, v204
	v_cmp_le_u32_e32 vcc, s8, v203
	s_bcnt1_i32_b64 s0, s[0:1]
	s_bcnt1_i32_b64 s1, vcc
	s_add_i32 m0, m0, s0
	s_add_i32 m0, m0, s1
	v_cmp_le_u32_e64 s[0:1], s8, v206
	v_cmp_le_u32_e32 vcc, s8, v205
	s_bcnt1_i32_b64 s0, s[0:1]
	s_bcnt1_i32_b64 s1, vcc
	s_add_i32 m0, m0, s0
	s_add_i32 m0, m0, s1
	v_cmp_le_u32_e64 s[0:1], s8, v207
	v_cmp_le_u32_e32 vcc, s8, v183
	s_bcnt1_i32_b64 s0, s[0:1]
	s_bcnt1_i32_b64 s1, vcc
	s_add_i32 m0, m0, s0
	s_add_i32 m0, m0, s1
	v_cmp_le_u32_e64 s[0:1], s8, v209
	v_cmp_le_u32_e32 vcc, s8, v208
	s_bcnt1_i32_b64 s0, s[0:1]
	s_bcnt1_i32_b64 s1, vcc
	s_add_i32 m0, m0, s0
	s_add_i32 m0, m0, s1
	v_cmp_le_u32_e64 s[0:1], s8, v211
	v_cmp_le_u32_e32 vcc, s8, v210
	s_bcnt1_i32_b64 s0, s[0:1]
	s_bcnt1_i32_b64 s1, vcc
	s_add_i32 m0, m0, s0
	s_add_i32 m0, m0, s1
	v_cmp_le_u32_e64 s[0:1], s8, v213
	v_cmp_le_u32_e32 vcc, s8, v212
	s_bcnt1_i32_b64 s0, s[0:1]
	s_bcnt1_i32_b64 s1, vcc
	s_add_i32 m0, m0, s0
	s_add_i32 m0, m0, s1
	v_cmp_le_u32_e64 s[0:1], s8, v215
	v_cmp_le_u32_e32 vcc, s8, v214
	s_bcnt1_i32_b64 s0, s[0:1]
	s_bcnt1_i32_b64 s1, vcc
	s_add_i32 m0, m0, s0
	s_add_i32 m0, m0, s1
	v_cmp_le_u32_e64 s[0:1], s8, v217
	v_cmp_le_u32_e32 vcc, s8, v216
	s_bcnt1_i32_b64 s0, s[0:1]
	s_bcnt1_i32_b64 s1, vcc
	s_add_i32 m0, m0, s0
	s_add_i32 m0, m0, s1
	v_cmp_le_u32_e64 s[0:1], s8, v219
	v_cmp_le_u32_e32 vcc, s8, v218
	s_bcnt1_i32_b64 s0, s[0:1]
	s_bcnt1_i32_b64 s1, vcc
	s_add_i32 m0, m0, s0
	s_add_i32 m0, m0, s1
	v_cmp_le_u32_e64 s[0:1], s8, v221
	v_cmp_le_u32_e32 vcc, s8, v220
	s_bcnt1_i32_b64 s0, s[0:1]
	s_bcnt1_i32_b64 s1, vcc
	s_add_i32 m0, m0, s0
	s_add_i32 m0, m0, s1
	s_cmp_gt_u32 m0, 0xff
	s_cselect_b32 s4, s8, s4
	s_add_i32 s5, s5, -1
	s_cmp_lt_u32 s5, 2
	s_cbranch_scc0 .LBB0_987
